# grid barrier: acquire invalidate issued right after the arrival atomic (overlaps the wait; the CU issues no L1-allocating loads until release), last leader does not wait for its release atomics
# speedup vs baseline: 1.0790x; 1.0011x over previous
.LBB0_517:
	s_cmp_lt_i32 s24, 2
	s_cselect_b64 s[0:1], -1, 0
	s_xor_b64 s[6:7], s[6:7], -1
	s_or_b64 s[0:1], s[0:1], s[6:7]
	s_and_b64 vcc, exec, s[0:1]
	s_cbranch_vccnz .LBB0_5
	s_cmp_lg_u32 s24, 2
	s_mov_b64 s[6:7], -1
	s_cbranch_scc0 .LBB0_526
	s_waitcnt vmcnt(0) lgkmcnt(0)
	v_readlane_b32 s28, v254, 41
	v_readlane_b32 s29, v254, 42
	v_readlane_b32 s0, v254, 28
	s_load_dwordx2 s[28:29], s[28:29], 0x120
	s_add_i32 s13, s0, 1
	s_waitcnt vmcnt(0)
	s_barrier
	s_mov_b64 s[6:7], exec
	v_readlane_b32 s0, v254, 29
	v_readlane_b32 s1, v254, 30
	s_and_b64 s[0:1], s[6:7], s[0:1]
	s_mov_b64 exec, s[0:1]
	s_cbranch_execz .LBB0_525
	s_getreg_b32 s8, hwreg(HW_REG_XCC_ID, 0, 4)
	s_and_b32 s8, s8, 7
	s_lshr_b32 s9, s54, 3
	v_mov_b32_e32 v1, 1
	s_mul_i32 s9, s9, s13
	s_lshl_b32 s11, s8, 4
	s_lshl_b32 s18, s8, 3
	s_add_u32 s18, s18, 0x80
	v_mov_b32_e32 v3, s11
	v_mov_b32_e32 v5, s18
	s_waitcnt lgkmcnt(0)
	s_add_u32 s0, s28, 0x198000
	s_addc_u32 s1, s29, 0
	global_atomic_add v3, v3, v1, s[0:1] sc0
	buffer_inv sc1
	s_mov_b32 s20, 0
	s_lshl_b32 s21, s13, 3
	s_waitcnt vmcnt(1)
	v_add_u32_e32 v3, 1, v3
	v_cmp_eq_u32_e32 vcc, s9, v3
	s_cbranch_vccz .Lxb_early
	buffer_wbl2 sc1
	s_waitcnt vmcnt(0)
	global_atomic_add v3, v2, v1, s[0:1] offset:192 sc0
	s_waitcnt vmcnt(0)
	v_add_u32_e32 v3, 1, v3
	v_cmp_eq_u32_e32 vcc, s21, v3
	s_cbranch_vccz .Lxb_fspin
	global_atomic_add v2, v1, s[0:1] offset:128
	global_atomic_add v2, v1, s[0:1] offset:136
	global_atomic_add v2, v1, s[0:1] offset:144
	global_atomic_add v2, v1, s[0:1] offset:152
	global_atomic_add v2, v1, s[0:1] offset:160
	global_atomic_add v2, v1, s[0:1] offset:168
	global_atomic_add v2, v1, s[0:1] offset:176
	global_atomic_add v2, v1, s[0:1] offset:184
	s_branch .Lxb_done
.Lxb_early:
.Lxb_fspin:
	global_load_dword v3, v5, s[0:1] sc1
	s_waitcnt vmcnt(0)
	v_cmp_le_u32_e32 vcc, s13, v3
	s_cbranch_vccnz .Lxb_facq
	s_sleep 1
	s_add_u32 s20, s20, 1
	s_cmp_lt_u32 s20, 0x2000
	s_cbranch_scc1 .Lxb_fspin
	v_mov_b32_e32 v1, 0x100000
	global_atomic_add v2, v1, s[0:1] offset:128
	global_atomic_add v2, v1, s[0:1] offset:136
	global_atomic_add v2, v1, s[0:1] offset:144
	global_atomic_add v2, v1, s[0:1] offset:152
	global_atomic_add v2, v1, s[0:1] offset:160
	global_atomic_add v2, v1, s[0:1] offset:168
	global_atomic_add v2, v1, s[0:1] offset:176
	global_atomic_add v2, v1, s[0:1] offset:184
.Lxb_facq:
	s_waitcnt vmcnt(0)
.Lxb_done:
.LBB0_525:
	s_or_b64 exec, exec, s[6:7]
	s_mov_b64 s[6:7], 0
	s_waitcnt lgkmcnt(0)
	s_barrier
